# phase-0 mod GEMV: 32 row loads in flight per trip (4 trips instead of 16), same FMA order; on top of the SGPR-base DMA / no-setprio GEMM loops
# baseline (speedup 1.0000x reference)
; __device__ __forceinline__ void phase0(const Ptrs& P, ldsp lds, int tid, int lane, int wave, int G) {
;     ...
;     for (int u = blockIdx.x; u < 384; u += G) {
;         const int kc = u / 48, l = (u % 48) / 24, cc = u % 24, col = cc * 256 + (tid & 255), kh = tid >> 8, r0 = kc * 256 + kh * 128;
;         const float* w = P.w_ada + (size_t)l * DMODEL * 6144 + (size_t)r0 * 6144 + col;
;         float a0 = 0.f, a1 = 0.f, a2 = 0.f, a3 = 0.f;
; #pragma unroll 2
;         for (int d = 0; d < 128; d += 4) {
;             a0 += sc[r0 + d] * w[(size_t)d * 6144]; a1 += sc[r0 + d + 1] * w[(size_t)(d + 1) * 6144];
;             a2 += sc[r0 + d + 2] * w[(size_t)(d + 2) * 6144]; a3 += sc[r0 + d + 3] * w[(size_t)(d + 3) * 6144]; }
;         const float a = (a0 + a1) + (a2 + a3);
.LBB0_24:
	s_mul_hi_i32 s24, s29, 0x2aaaaaab
	s_ashr_i32 s30, s24, 3
	s_lshr_b32 s25, s24, 31
	s_add_i32 s30, s30, s25
	s_mul_i32 s31, s30, 48
	s_sub_i32 s31, s29, s31
	s_mul_i32 s31, s31, 43
	s_sext_i32_i16 s34, s31
	s_lshr_b32 s24, s24, 2
	s_ashr_i32 s34, s34, 10
	s_bfe_u32 s31, s31, 0x1000f
	s_add_i32 s24, s24, s25
	s_add_i32 s34, s34, s31
	s_mul_i32 s24, s24, 24
	s_sext_i32_i16 s31, s34
	s_sub_i32 s24, s29, s24
	v_lshl_or_b32 v2, s24, 8, v1
	s_mul_i32 s24, s31, 0xc00000
	s_ashr_i32 s25, s24, 31
	s_lshl_b64 s[24:25], s[24:25], 2
	v_lshl_add_u32 v6, s30, 8, v12
	v_mov_b64_e32 v[4:5], s[24:25]
	v_ashrrev_i32_e32 v3, 31, v2
	v_mad_i64_i32 v[4:5], s[24:25], v6, s28, v[4:5]
	v_lshl_add_u32 v15, v6, 2, 0
	v_lshl_add_u64 v[4:5], v[2:3], 2, v[4:5]
	v_mov_b32_e32 v6, 0
	v_lshl_add_u64 v[4:5], s[8:9], 0, v[4:5]
	s_mov_b32 s24, -4
	v_mov_b32_e32 v7, v6
	v_mov_b32_e32 v8, v6
	v_mov_b32_e32 v9, v6
	v_add_co_u32_e32 v16, vcc, 0xfffd6000, v4
	s_mov_b64 s[100:101], 0x6000
	s_nop 0
	v_addc_co_u32_e32 v17, vcc, -1, v5, vcc
.LBB0_25:
	global_load_dword v40, v[16:17], off
	v_lshl_add_u64 v[16:17], v[16:17], 0, s[100:101]
	global_load_dword v41, v[16:17], off
	v_lshl_add_u64 v[16:17], v[16:17], 0, s[100:101]
	global_load_dword v42, v[16:17], off
	v_lshl_add_u64 v[16:17], v[16:17], 0, s[100:101]
	global_load_dword v43, v[16:17], off
	v_lshl_add_u64 v[16:17], v[16:17], 0, s[100:101]
	global_load_dword v44, v[16:17], off
	v_lshl_add_u64 v[16:17], v[16:17], 0, s[100:101]
	global_load_dword v45, v[16:17], off
	v_lshl_add_u64 v[16:17], v[16:17], 0, s[100:101]
	global_load_dword v46, v[16:17], off
	v_lshl_add_u64 v[16:17], v[16:17], 0, s[100:101]
	global_load_dword v47, v[16:17], off
	v_lshl_add_u64 v[16:17], v[16:17], 0, s[100:101]
	global_load_dword v48, v[16:17], off
	v_lshl_add_u64 v[16:17], v[16:17], 0, s[100:101]
	global_load_dword v49, v[16:17], off
	v_lshl_add_u64 v[16:17], v[16:17], 0, s[100:101]
	global_load_dword v50, v[16:17], off
	v_lshl_add_u64 v[16:17], v[16:17], 0, s[100:101]
	global_load_dword v51, v[16:17], off
	v_lshl_add_u64 v[16:17], v[16:17], 0, s[100:101]
	global_load_dword v52, v[16:17], off
	v_lshl_add_u64 v[16:17], v[16:17], 0, s[100:101]
	global_load_dword v53, v[16:17], off
	v_lshl_add_u64 v[16:17], v[16:17], 0, s[100:101]
	global_load_dword v54, v[16:17], off
	v_lshl_add_u64 v[16:17], v[16:17], 0, s[100:101]
	global_load_dword v55, v[16:17], off
	v_lshl_add_u64 v[16:17], v[16:17], 0, s[100:101]
	global_load_dword v56, v[16:17], off
	v_lshl_add_u64 v[16:17], v[16:17], 0, s[100:101]
	global_load_dword v57, v[16:17], off
	v_lshl_add_u64 v[16:17], v[16:17], 0, s[100:101]
	global_load_dword v58, v[16:17], off
	v_lshl_add_u64 v[16:17], v[16:17], 0, s[100:101]
	global_load_dword v59, v[16:17], off
	v_lshl_add_u64 v[16:17], v[16:17], 0, s[100:101]
	global_load_dword v60, v[16:17], off
	v_lshl_add_u64 v[16:17], v[16:17], 0, s[100:101]
	global_load_dword v61, v[16:17], off
	v_lshl_add_u64 v[16:17], v[16:17], 0, s[100:101]
	global_load_dword v62, v[16:17], off
	v_lshl_add_u64 v[16:17], v[16:17], 0, s[100:101]
	global_load_dword v63, v[16:17], off
	v_lshl_add_u64 v[16:17], v[16:17], 0, s[100:101]
	global_load_dword v64, v[16:17], off
	v_lshl_add_u64 v[16:17], v[16:17], 0, s[100:101]
	global_load_dword v65, v[16:17], off
	v_lshl_add_u64 v[16:17], v[16:17], 0, s[100:101]
	global_load_dword v66, v[16:17], off
	v_lshl_add_u64 v[16:17], v[16:17], 0, s[100:101]
	global_load_dword v67, v[16:17], off
	v_lshl_add_u64 v[16:17], v[16:17], 0, s[100:101]
	global_load_dword v68, v[16:17], off
	v_lshl_add_u64 v[16:17], v[16:17], 0, s[100:101]
	global_load_dword v69, v[16:17], off
	v_lshl_add_u64 v[16:17], v[16:17], 0, s[100:101]
	global_load_dword v70, v[16:17], off
	v_lshl_add_u64 v[16:17], v[16:17], 0, s[100:101]
	global_load_dword v71, v[16:17], off
	v_lshl_add_u64 v[16:17], v[16:17], 0, s[100:101]
	ds_read_b128 v[72:75], v15
	ds_read_b128 v[76:79], v15 offset:16
	ds_read_b128 v[80:83], v15 offset:32
	ds_read_b128 v[84:87], v15 offset:48
	ds_read_b128 v[88:91], v15 offset:64
	ds_read_b128 v[92:95], v15 offset:80
	ds_read_b128 v[96:99], v15 offset:96
	ds_read_b128 v[100:103], v15 offset:112
	v_add_u32_e32 v15, 0x80, v15
	s_waitcnt vmcnt(30) lgkmcnt(7)
	v_pk_fma_f32 v[6:7], v[72:73], v[40:41], v[6:7]
	s_waitcnt vmcnt(28)
	v_pk_fma_f32 v[8:9], v[74:75], v[42:43], v[8:9]
	s_waitcnt vmcnt(26) lgkmcnt(6)
	v_pk_fma_f32 v[6:7], v[76:77], v[44:45], v[6:7]
	s_waitcnt vmcnt(24)
	v_pk_fma_f32 v[8:9], v[78:79], v[46:47], v[8:9]
	s_waitcnt vmcnt(22) lgkmcnt(5)
	v_pk_fma_f32 v[6:7], v[80:81], v[48:49], v[6:7]
	s_waitcnt vmcnt(20)
	v_pk_fma_f32 v[8:9], v[82:83], v[50:51], v[8:9]
	s_waitcnt vmcnt(18) lgkmcnt(4)
	v_pk_fma_f32 v[6:7], v[84:85], v[52:53], v[6:7]
	s_waitcnt vmcnt(16)
	v_pk_fma_f32 v[8:9], v[86:87], v[54:55], v[8:9]
	s_waitcnt vmcnt(14) lgkmcnt(3)
	v_pk_fma_f32 v[6:7], v[88:89], v[56:57], v[6:7]
	s_waitcnt vmcnt(12)
	v_pk_fma_f32 v[8:9], v[90:91], v[58:59], v[8:9]
	s_waitcnt vmcnt(10) lgkmcnt(2)
	v_pk_fma_f32 v[6:7], v[92:93], v[60:61], v[6:7]
	s_waitcnt vmcnt(8)
	v_pk_fma_f32 v[8:9], v[94:95], v[62:63], v[8:9]
	s_waitcnt vmcnt(6) lgkmcnt(1)
	v_pk_fma_f32 v[6:7], v[96:97], v[64:65], v[6:7]
	s_waitcnt vmcnt(4)
	v_pk_fma_f32 v[8:9], v[98:99], v[66:67], v[8:9]
	s_waitcnt vmcnt(2) lgkmcnt(0)
	v_pk_fma_f32 v[6:7], v[100:101], v[68:69], v[6:7]
	s_waitcnt vmcnt(0)
	v_pk_fma_f32 v[8:9], v[102:103], v[70:71], v[8:9]
	s_add_i32 s24, s24, 32
	s_cmpk_gt_u32 s24, 0x7b
	s_cbranch_scc0 .LBB0_25
	v_add_f32_e32 v3, v8, v9
	v_add_f32_e32 v4, v6, v7
	v_add_f32_e32 v3, v4, v3
	s_barrier
	s_and_saveexec_b64 s[24:25], s[4:5]
	ds_write_b32 v13, v3 offset:8192
	s_or_b64 exec, exec, s[24:25]
	s_waitcnt lgkmcnt(0)
	s_barrier
	s_and_saveexec_b64 s[24:25], s[6:7]
	s_cbranch_execz .LBB0_23
	ds_read_b32 v4, v14 offset:8192
	s_add_i32 s34, s29, 47
	s_cmpk_gt_u32 s34, 0x5e
	v_mov_b32_e32 v5, 0
	s_cbranch_scc1 .LBB0_22
	s_mul_i32 s34, s31, 0x1800
	v_add_u32_e32 v6, s34, v2
	v_ashrrev_i32_e32 v7, 31, v6
	v_lshl_add_u64 v[6:7], v[6:7], 2, s[26:27]
	global_load_dword v5, v[6:7], off
	s_branch .LBB0_22
